# m1+m2+m6: grid-barrier invalidate issued while waiting for the release instead of after it
# baseline (speedup 1.0000x reference)
; __device__ __forceinline__ unsigned xb_ld(unsigned* p)              { return __hip_atomic_load(p, __ATOMIC_RELAXED, __HIP_MEMORY_SCOPE_AGENT); }
; __device__ __forceinline__ unsigned xb_add(unsigned* p, unsigned v) { return __hip_atomic_fetch_add(p, v, __ATOMIC_RELAXED, __HIP_MEMORY_SCOPE_AGENT); }
; #define XB_SPIN(cond, bar) do { unsigned _sp = 0; while (cond) { __builtin_amdgcn_s_sleep(0); \
;     if ((++_sp & 255u) == 0u) { if (xb_ld(&(bar)[XB_TMO])) break; if (_sp > XB_SPIN_CAP) { atomicAdd(&(bar)[XB_TMO], 1u); break; } } } } while (0)
; __device__ __forceinline__ void xcd_barrier(const XcdBarrier& b) {
;     ...
;         const unsigned old = xb_add(&bar[XB_XSUB(b.x)], 1u);
;         const unsigned gen = old / nloc;
;         if (old + 1u == (gen + 1u) * nloc) {
;             __builtin_amdgcn_fence(__ATOMIC_RELEASE, "agent");
;             asm volatile("s_waitcnt vmcnt(0)" ::: "memory");
;             const unsigned og = xb_add(&bar[XB_TOP], 1u);
;             const unsigned tg = og / nx;
;             if (og + 1u == (tg + 1u) * nx) xb_add(&bar[XB_TOPGEN], 1u);
;             else XB_SPIN(xb_ld(&bar[XB_TOPGEN]) == tg, bar);
;             __builtin_amdgcn_fence(__ATOMIC_ACQUIRE, "agent");
;             xb_add(&bar[XB_XGEN(b.x)], 1u);
;             asm volatile("s_waitcnt vmcnt(0)" ::: "memory");
;         } else {
;             XB_SPIN(xb_ld(&bar[XB_XGEN(b.x)]) == gen, bar);
.LBB0_742:
	s_or_b64 exec, exec, s[12:13]
	v_cvt_f32_u32_e32 v4, v2
	s_waitcnt vmcnt(0)
	v_readfirstlane_b32 s1, v3
	v_sub_u32_e32 v3, 0, v2
	v_rcp_iflag_f32_e32 v4, v4
	v_add_u32_e32 v5, s1, v1
	v_mul_f32_e32 v4, 0x4f7ffffe, v4
	v_cvt_u32_f32_e32 v4, v4
	v_mul_lo_u32 v1, v3, v4
	v_mul_hi_u32 v1, v4, v1
	v_add_u32_e32 v1, v4, v1
	v_mul_hi_u32 v1, v5, v1
	v_mul_lo_u32 v3, v1, v2
	v_sub_u32_e32 v3, v5, v3
	v_add_u32_e32 v4, 1, v1
	v_cmp_ge_u32_e32 vcc, v3, v2
	s_nop 1
	v_cndmask_b32_e32 v1, v1, v4, vcc
	v_sub_u32_e32 v4, v3, v2
	v_cndmask_b32_e32 v3, v3, v4, vcc
	v_add_u32_e32 v4, 1, v1
	v_cmp_ge_u32_e32 vcc, v3, v2
	v_add_u32_e32 v3, 1, v5
	s_nop 0
	v_cndmask_b32_e32 v1, v1, v4, vcc
	v_mul_lo_u32 v4, v2, v1
	v_add_u32_e32 v2, v4, v2
	v_cmp_ne_u32_e32 vcc, v3, v2
	s_and_saveexec_b64 s[10:11], vcc
	s_xor_b64 s[10:11], exec, s[10:11]
	s_cbranch_execz .LBB0_756
	buffer_inv sc1
	s_waitcnt lgkmcnt(0)
	v_mov_b32_e32 v0, 0x2000
	global_load_dword v0, v0, s[8:9] offset:1024 sc1
	s_add_u32 s16, s8, 0x2400
	s_addc_u32 s17, s9, 0
	s_waitcnt vmcnt(0)
	v_cmp_eq_u32_e32 vcc, v0, v1
	s_and_saveexec_b64 s[12:13], vcc
	s_cbranch_execz .LBB0_755
	s_add_u32 s14, s30, 0x80200
	s_addc_u32 s15, s31, 0
	s_mov_b32 s1, 1
	s_mov_b64 s[18:19], 0
	s_branch .LBB0_746

; __device__ __forceinline__ unsigned xb_ld(unsigned* p)              { return __hip_atomic_load(p, __ATOMIC_RELAXED, __HIP_MEMORY_SCOPE_AGENT); }
; __device__ __forceinline__ unsigned xb_add(unsigned* p, unsigned v) { return __hip_atomic_fetch_add(p, v, __ATOMIC_RELAXED, __HIP_MEMORY_SCOPE_AGENT); }
; #define XB_SPIN(cond, bar) do { unsigned _sp = 0; while (cond) { __builtin_amdgcn_s_sleep(0); \
;     if ((++_sp & 255u) == 0u) { if (xb_ld(&(bar)[XB_TMO])) break; if (_sp > XB_SPIN_CAP) { atomicAdd(&(bar)[XB_TMO], 1u); break; } } } } while (0)
; __device__ __forceinline__ void xcd_barrier(const XcdBarrier& b) {
;     ...
;         if (old + 1u == (gen + 1u) * nloc) {
;             __builtin_amdgcn_fence(__ATOMIC_RELEASE, "agent");
;             asm volatile("s_waitcnt vmcnt(0)" ::: "memory");
;             const unsigned og = xb_add(&bar[XB_TOP], 1u);
;             const unsigned tg = og / nx;
;             if (og + 1u == (tg + 1u) * nx) xb_add(&bar[XB_TOPGEN], 1u);
;             else XB_SPIN(xb_ld(&bar[XB_TOPGEN]) == tg, bar);
;             __builtin_amdgcn_fence(__ATOMIC_ACQUIRE, "agent");
.LBB0_755:
	s_or_b64 exec, exec, s[12:13]
	s_waitcnt vmcnt(0)
	s_waitcnt vmcnt(0)
.LBB0_756:
	s_andn2_saveexec_b64 s[10:11], s[10:11]
	s_cbranch_execz .LBB0_776
	s_mov_b64 s[10:11], exec
	buffer_wbl2 sc1
	buffer_inv sc1
	s_waitcnt lgkmcnt(0)
	s_waitcnt vmcnt(0)
	v_mbcnt_lo_u32_b32 v1, s10, 0
	v_mbcnt_hi_u32_b32 v1, s11, v1
	v_cmp_eq_u32_e32 vcc, 0, v1
	s_and_saveexec_b64 s[12:13], vcc
	s_cbranch_execz .LBB0_759
	s_bcnt1_i32_b64 s1, s[10:11]
	v_mov_b32_e32 v2, s1
	v_mov_b32_e32 v3, 0x83000
	global_atomic_add v2, v3, v2, s[30:31] offset:1024 sc0

; __device__ __forceinline__ unsigned xb_ld(unsigned* p)              { return __hip_atomic_load(p, __ATOMIC_RELAXED, __HIP_MEMORY_SCOPE_AGENT); }
; __device__ __forceinline__ unsigned xb_add(unsigned* p, unsigned v) { return __hip_atomic_fetch_add(p, v, __ATOMIC_RELAXED, __HIP_MEMORY_SCOPE_AGENT); }
; #define XB_SPIN(cond, bar) do { unsigned _sp = 0; while (cond) { __builtin_amdgcn_s_sleep(0); \
;     if ((++_sp & 255u) == 0u) { if (xb_ld(&(bar)[XB_TMO])) break; if (_sp > XB_SPIN_CAP) { atomicAdd(&(bar)[XB_TMO], 1u); break; } } } } while (0)
; __device__ __forceinline__ void xcd_barrier(const XcdBarrier& b) {
;     ...
;             else XB_SPIN(xb_ld(&bar[XB_TOPGEN]) == tg, bar);
;             __builtin_amdgcn_fence(__ATOMIC_ACQUIRE, "agent");
;             xb_add(&bar[XB_XGEN(b.x)], 1u);
;             asm volatile("s_waitcnt vmcnt(0)" ::: "memory");
.LBB0_773:
	s_or_b64 exec, exec, s[10:11]
	s_mov_b64 s[10:11], exec
	v_mbcnt_lo_u32_b32 v0, s10, 0
	v_mbcnt_hi_u32_b32 v0, s11, v0
	v_cmp_eq_u32_e32 vcc, 0, v0
	s_waitcnt vmcnt(0)
	s_and_saveexec_b64 s[12:13], vcc
	s_cbranch_execz .LBB0_775
	s_bcnt1_i32_b64 s1, s[10:11]
	v_mov_b32_e32 v0, s1
	v_mov_b32_e32 v1, 0x2000
	global_atomic_add v1, v0, s[8:9] offset:1024
